# E5: seam acquire-invalidate issued at arrival by wave 1 (overlaps barrier protocol), late inv removed; on E1+E2
# speedup vs baseline: 1.0182x; 1.0071x over previous
.LBB0_109:
	v_readlane_b32 s0, v244, 3
	v_readlane_b32 s1, v244, 4
	s_cmp_gt_i32 s1, 1
	s_cselect_b64 s[0:1], -1, 0
	s_and_b64 s[4:5], s[4:5], s[0:1]
	s_andn2_b64 vcc, exec, s[4:5]
	s_cbranch_vccnz .LBB0_163
	s_waitcnt vmcnt(0)
	s_waitcnt lgkmcnt(0)
	s_barrier
	s_getreg_b32 s3, hwreg(HW_REG_HW_ID, 0, 6)
	s_and_b32 s3, s3, 63
	s_lshl_b32 s3, s3, 2
	s_add_i32 s3, s3, 0
	s_mov_b64 s[4:5], src_shared_base
	s_add_i32 s3, s3, 0x23e00
	v_mov_b32_e32 v2, s3
	v_mov_b32_e32 v3, s5
	flat_load_dword v2, v[2:3] sc0 sc1
	s_waitcnt vmcnt(0) lgkmcnt(0)
	v_readfirstlane_b32 s3, v2
	s_cmp_lg_u32 s3, 1
	s_cbranch_scc1 .Learlyinv_skip0
	buffer_inv sc1
	s_waitcnt vmcnt(0)
.Learlyinv_skip0:
	s_lshl_b32 s3, s3, 6
	s_sub_i32 s3, 0, s3
	v_cmp_eq_u32_e32 vcc, s3, v217
	s_and_saveexec_b64 s[4:5], vcc
	s_cbranch_execz .LBB0_162
	s_add_i32 s3, 0, 0x23f20
	v_mov_b32_e32 v2, s3
	s_waitcnt vmcnt(0) expcnt(0) lgkmcnt(0)
	ds_read_b32 v4, v2
	s_add_i32 s3, 0, 0x23f24
	v_mov_b32_e32 v2, s3
	ds_read_b32 v2, v2
	s_waitcnt lgkmcnt(1)
	v_cmp_ne_u32_e32 vcc, 0, v4
	s_cbranch_vccnz .LBB0_126
	s_add_u32 s6, s82, 0x40200
	s_addc_u32 s7, s83, 0
	s_add_u32 s16, s82, 0x40400
	s_addc_u32 s17, s83, 0
	s_add_u32 s18, s82, 0x40500
	s_addc_u32 s19, s83, 0
	s_add_u32 s24, s82, 0x40600
	s_addc_u32 s25, s83, 0
	s_add_u32 s26, s82, 0x40700
	s_addc_u32 s27, s83, 0
	s_add_u32 s28, s82, 0x40800
	s_addc_u32 s29, s83, 0
	s_add_u32 s30, s82, 0x40900
	s_addc_u32 s31, s83, 0
	s_add_u32 s34, s82, 0x40a00
	s_addc_u32 s35, s83, 0
	s_add_u32 s36, s82, 0x40b00
	s_addc_u32 s37, s83, 0
	s_add_u32 s38, s82, 0x40c00
	s_addc_u32 s39, s83, 0
	s_add_u32 s40, s82, 0x40d00
	s_addc_u32 s41, s83, 0
	s_add_u32 s42, s82, 0x40e00
	s_addc_u32 s43, s83, 0
	s_add_u32 s44, s82, 0x40f00
	s_addc_u32 s45, s83, 0
	s_add_u32 s46, s82, 0x41000
	s_addc_u32 s47, s83, 0
	s_add_u32 s48, s82, 0x41100
	s_addc_u32 s49, s83, 0
	s_add_u32 s62, s82, 0x41200
	v_readlane_b32 s3, v244, 2
	s_addc_u32 s63, s83, 0
	s_mul_i32 s3, s89, s3
	s_add_u32 s76, s82, 0x41300
	s_mul_i32 s3, s3, s88
	s_addc_u32 s77, s83, 0
	s_mov_b32 s33, 1
	v_mov_b32_e32 v18, 0
	s_branch .LBB0_114

.LBB0_141:
	s_or_b64 exec, exec, s[18:19]
	s_waitcnt vmcnt(0)
	s_waitcnt vmcnt(0)

.LBB0_159:
	s_or_b64 exec, exec, s[16:17]
	s_mov_b64 s[16:17], exec
	v_mbcnt_lo_u32_b32 v2, s16, 0
	v_mbcnt_hi_u32_b32 v2, s17, v2
	v_cmp_eq_u32_e32 vcc, 0, v2
	s_waitcnt vmcnt(0)
	s_and_saveexec_b64 s[18:19], vcc
	s_cbranch_execz .LBB0_161
	s_bcnt1_i32_b64 s3, s[16:17]
	v_mov_b32_e32 v2, 0x2000
	v_mov_b32_e32 v3, s3
	global_atomic_add v2, v3, s[6:7] offset:1024

.LBB0_256:
	v_readlane_b32 s0, v244, 3
	v_readlane_b32 s1, v244, 4
	s_cmp_gt_i32 s1, 2
	s_cselect_b64 s[0:1], -1, 0
	s_and_b64 s[4:5], s[6:7], s[0:1]
	s_andn2_b64 vcc, exec, s[4:5]
	s_cbranch_vccnz .LBB0_310
	s_waitcnt vmcnt(0)
	s_waitcnt vmcnt(0)
	s_barrier
	s_getreg_b32 s3, hwreg(HW_REG_HW_ID, 0, 6)
	s_and_b32 s3, s3, 63
	s_lshl_b32 s3, s3, 2
	s_add_i32 s3, s3, 0
	s_mov_b64 s[4:5], src_shared_base
	s_add_i32 s3, s3, 0x23e00
	v_mov_b32_e32 v2, s3
	v_mov_b32_e32 v3, s5
	flat_load_dword v2, v[2:3] sc0 sc1
	s_waitcnt vmcnt(0) lgkmcnt(0)
	v_readfirstlane_b32 s3, v2
	s_cmp_lg_u32 s3, 1
	s_cbranch_scc1 .Learlyinv_skip1
	buffer_inv sc1
	s_waitcnt vmcnt(0)
.Learlyinv_skip1:
	s_lshl_b32 s3, s3, 6
	s_sub_i32 s3, 0, s3
	v_cmp_eq_u32_e32 vcc, s3, v217
	s_and_saveexec_b64 s[4:5], vcc
	s_cbranch_execz .LBB0_309
	s_add_i32 s3, 0, 0x23f20
	v_mov_b32_e32 v2, s3
	s_waitcnt vmcnt(0) expcnt(0) lgkmcnt(0)
	ds_read_b32 v4, v2
	s_add_i32 s3, 0, 0x23f24
	v_mov_b32_e32 v2, s3
	ds_read_b32 v2, v2
	s_waitcnt lgkmcnt(1)
	v_cmp_ne_u32_e32 vcc, 0, v4
	s_cbranch_vccnz .LBB0_273
	v_readlane_b32 s6, v244, 0
	v_readlane_b32 s7, v244, 1
	s_load_dword s6, s[6:7], 0x14
	s_mov_b32 s3, 1
	v_mov_b32_e32 v18, 0
	s_waitcnt lgkmcnt(0)
	s_lshr_b32 s16, s6, 16
	s_and_b32 s6, s6, 0xffff
	s_cmp_lg_u32 s6, 0
	s_cselect_b64 s[6:7], -1, 0
	s_cmp_lg_u64 s[6:7], 0
	s_addc_u32 s6, s89, 0
	s_cmp_lg_u32 s16, 0
	s_mul_i32 s33, s6, s88
	s_cselect_b64 s[6:7], -1, 0
	s_cmp_lg_u64 s[6:7], 0
	v_readlane_b32 s6, v244, 2
	s_addc_u32 s6, s6, 0
	s_mul_i32 s33, s33, s6
	s_add_u32 s6, s82, 0x40200
	s_addc_u32 s7, s83, 0
	s_add_u32 s16, s82, 0x40400
	s_addc_u32 s17, s83, 0
	s_add_u32 s18, s82, 0x40500
	s_addc_u32 s19, s83, 0
	s_add_u32 s24, s82, 0x40600
	s_addc_u32 s25, s83, 0
	s_add_u32 s26, s82, 0x40700
	s_addc_u32 s27, s83, 0
	s_add_u32 s28, s82, 0x40800
	s_addc_u32 s29, s83, 0
	s_add_u32 s30, s82, 0x40900
	s_addc_u32 s31, s83, 0
	s_add_u32 s34, s82, 0x40a00
	s_addc_u32 s35, s83, 0
	s_add_u32 s36, s82, 0x40b00
	s_addc_u32 s37, s83, 0
	s_add_u32 s38, s82, 0x40c00
	s_addc_u32 s39, s83, 0
	s_add_u32 s40, s82, 0x40d00
	s_addc_u32 s41, s83, 0
	s_add_u32 s42, s82, 0x40e00
	s_addc_u32 s43, s83, 0
	s_add_u32 s44, s82, 0x40f00
	s_addc_u32 s45, s83, 0
	s_add_u32 s46, s82, 0x41000
	s_addc_u32 s47, s83, 0
	s_add_u32 s48, s82, 0x41100
	s_addc_u32 s49, s83, 0
	s_add_u32 s76, s82, 0x41200
	s_addc_u32 s77, s83, 0
	s_add_u32 s78, s82, 0x41300
	s_addc_u32 s79, s83, 0
	s_branch .LBB0_261

.LBB0_574:
	v_readlane_b32 s0, v244, 3
	v_readlane_b32 s1, v244, 4
	s_cmp_gt_i32 s1, 3
	s_cselect_b64 s[0:1], -1, 0
	s_and_b64 s[4:5], s[16:17], s[0:1]
	s_andn2_b64 vcc, exec, s[4:5]
	s_cbranch_vccnz .LBB0_628
	s_waitcnt vmcnt(0)
	s_waitcnt vmcnt(0)
	s_barrier
	s_getreg_b32 s3, hwreg(HW_REG_HW_ID, 0, 6)
	s_and_b32 s3, s3, 63
	s_lshl_b32 s3, s3, 2
	s_add_i32 s3, s3, 0
	s_mov_b64 s[4:5], src_shared_base
	s_add_i32 s3, s3, 0x23e00
	v_mov_b32_e32 v4, s3
	v_mov_b32_e32 v5, s5
	flat_load_dword v3, v[4:5] sc0 sc1
	s_waitcnt vmcnt(0) lgkmcnt(0)
	v_readfirstlane_b32 s3, v3
	s_cmp_lg_u32 s3, 1
	s_cbranch_scc1 .Learlyinv_skip2
	buffer_inv sc1
	s_waitcnt vmcnt(0)
.Learlyinv_skip2:
	s_lshl_b32 s3, s3, 6
	s_sub_i32 s3, 0, s3
	v_cmp_eq_u32_e32 vcc, s3, v217
	s_and_saveexec_b64 s[4:5], vcc
	s_cbranch_execz .LBB0_627
	s_add_i32 s3, 0, 0x23f20
	v_mov_b32_e32 v3, s3
	s_waitcnt vmcnt(0) expcnt(0) lgkmcnt(0)
	ds_read_b32 v5, v3
	s_add_i32 s3, 0, 0x23f24
	v_mov_b32_e32 v3, s3
	ds_read_b32 v3, v3
	s_waitcnt lgkmcnt(1)
	v_cmp_ne_u32_e32 vcc, 0, v5
	s_cbranch_vccnz .LBB0_591
	v_readlane_b32 s6, v244, 0
	v_readlane_b32 s7, v244, 1
	s_load_dword s6, s[6:7], 0x14
	s_mov_b32 s3, 1
	v_mov_b32_e32 v19, 0
	s_waitcnt lgkmcnt(0)
	s_lshr_b32 s8, s6, 16
	s_and_b32 s6, s6, 0xffff
	s_cmp_lg_u32 s6, 0
	s_cselect_b64 s[6:7], -1, 0
	s_cmp_lg_u64 s[6:7], 0
	s_addc_u32 s6, s89, 0
	s_cmp_lg_u32 s8, 0
	s_mul_i32 s33, s6, s88
	s_cselect_b64 s[6:7], -1, 0
	s_cmp_lg_u64 s[6:7], 0
	v_readlane_b32 s6, v244, 2
	s_addc_u32 s6, s6, 0
	s_mul_i32 s33, s33, s6
	s_add_u32 s6, s82, 0x40200
	s_addc_u32 s7, s83, 0
	s_add_u32 s8, s82, 0x40400
	s_addc_u32 s9, s83, 0
	s_add_u32 s10, s82, 0x40500
	s_addc_u32 s11, s83, 0
	s_add_u32 s12, s82, 0x40600
	s_addc_u32 s13, s83, 0
	s_add_u32 s16, s82, 0x40700
	s_addc_u32 s17, s83, 0
	s_add_u32 s18, s82, 0x40800
	s_addc_u32 s19, s83, 0
	s_add_u32 s20, s82, 0x40900
	s_addc_u32 s21, s83, 0
	s_add_u32 s22, s82, 0x40a00
	s_addc_u32 s23, s83, 0
	s_add_u32 s24, s82, 0x40b00
	s_addc_u32 s25, s83, 0
	s_add_u32 s26, s82, 0x40c00
	s_addc_u32 s27, s83, 0
	s_add_u32 s28, s82, 0x40d00
	s_addc_u32 s29, s83, 0
	s_add_u32 s30, s82, 0x40e00
	s_addc_u32 s31, s83, 0
	s_add_u32 s34, s82, 0x40f00
	s_addc_u32 s35, s83, 0
	s_add_u32 s36, s82, 0x41000
	s_addc_u32 s37, s83, 0
	s_add_u32 s38, s82, 0x41100
	s_addc_u32 s39, s83, 0
	s_add_u32 s40, s82, 0x41200
	s_addc_u32 s41, s83, 0
	s_add_u32 s42, s82, 0x41300
	s_addc_u32 s43, s83, 0
	s_branch .LBB0_579

.LBB0_606:
	s_or_b64 exec, exec, s[10:11]
	s_waitcnt vmcnt(0)
	s_waitcnt vmcnt(0)

.LBB0_624:
	s_or_b64 exec, exec, s[8:9]
	s_mov_b64 s[8:9], exec
	v_mbcnt_lo_u32_b32 v3, s8, 0
	v_mbcnt_hi_u32_b32 v3, s9, v3
	v_cmp_eq_u32_e32 vcc, 0, v3
	s_waitcnt vmcnt(0)
	s_and_saveexec_b64 s[10:11], vcc
	s_cbranch_execz .LBB0_626
	s_bcnt1_i32_b64 s3, s[8:9]
	v_mov_b32_e32 v3, 0x2000
	v_mov_b32_e32 v4, s3
	global_atomic_add v3, v4, s[6:7] offset:1024

.LBB0_730:
	v_readlane_b32 s0, v244, 3
	v_readlane_b32 s1, v244, 4
	s_cmp_gt_i32 s1, 4
	s_cselect_b64 s[0:1], -1, 0
	s_and_b64 s[4:5], s[8:9], s[0:1]
	s_andn2_b64 vcc, exec, s[4:5]
	s_cbranch_vccnz .LBB0_784
	s_waitcnt vmcnt(0)
	s_waitcnt vmcnt(0) lgkmcnt(0)
	s_barrier
	s_getreg_b32 s3, hwreg(HW_REG_HW_ID, 0, 6)
	s_and_b32 s3, s3, 63
	s_lshl_b32 s3, s3, 2
	s_add_i32 s3, s3, 0
	s_mov_b64 s[4:5], src_shared_base
	s_add_i32 s3, s3, 0x23e00
	v_mov_b32_e32 v4, s3
	v_mov_b32_e32 v5, s5
	flat_load_dword v3, v[4:5] sc0 sc1
	s_waitcnt vmcnt(0) lgkmcnt(0)
	v_readfirstlane_b32 s3, v3
	s_cmp_lg_u32 s3, 1
	s_cbranch_scc1 .Learlyinv_skip3
	buffer_inv sc1
	s_waitcnt vmcnt(0)

.LBB0_827:
	v_readlane_b32 s0, v244, 3
	v_readlane_b32 s1, v244, 4
	s_cmp_gt_i32 s1, 5
	s_cselect_b64 s[0:1], -1, 0
	s_and_b64 s[4:5], s[4:5], s[0:1]
	s_andn2_b64 vcc, exec, s[4:5]
	s_cbranch_vccnz .LBB0_881
	s_waitcnt vmcnt(0)
	s_waitcnt vmcnt(0) lgkmcnt(0)
	s_barrier
	s_getreg_b32 s3, hwreg(HW_REG_HW_ID, 0, 6)
	s_and_b32 s3, s3, 63
	s_lshl_b32 s3, s3, 2
	s_add_i32 s3, s3, 0
	s_mov_b64 s[4:5], src_shared_base
	s_add_i32 s3, s3, 0x23e00
	v_mov_b32_e32 v4, s3
	v_mov_b32_e32 v5, s5
	flat_load_dword v3, v[4:5] sc0 sc1
	s_waitcnt vmcnt(0) lgkmcnt(0)
	v_readfirstlane_b32 s3, v3
	s_cmp_lg_u32 s3, 1
	s_cbranch_scc1 .Learlyinv_skip4
	buffer_inv sc1
	s_waitcnt vmcnt(0)

.LBB0_987:
	v_readlane_b32 s0, v244, 3
	v_readlane_b32 s1, v244, 4
	s_cmp_gt_i32 s1, 6
	s_cselect_b64 s[0:1], -1, 0
	s_and_b64 s[4:5], s[8:9], s[0:1]
	s_andn2_b64 vcc, exec, s[4:5]
	s_cbranch_vccnz .LBB0_1041
	s_waitcnt vmcnt(0)
	s_waitcnt vmcnt(0) lgkmcnt(0)
	s_barrier
	s_getreg_b32 s3, hwreg(HW_REG_HW_ID, 0, 6)
	s_and_b32 s3, s3, 63
	s_lshl_b32 s3, s3, 2
	s_add_i32 s3, s3, 0
	s_mov_b64 s[4:5], src_shared_base
	s_add_i32 s3, s3, 0x23e00
	v_mov_b32_e32 v4, s3
	v_mov_b32_e32 v5, s5
	flat_load_dword v3, v[4:5] sc0 sc1
	s_waitcnt vmcnt(0) lgkmcnt(0)
	v_readfirstlane_b32 s3, v3
	s_cmp_lg_u32 s3, 1
	s_cbranch_scc1 .Learlyinv_skip5
	buffer_inv sc1
	s_waitcnt vmcnt(0)
.Learlyinv_skip5:
	s_lshl_b32 s3, s3, 6
	s_sub_i32 s3, 0, s3
	v_cmp_eq_u32_e32 vcc, s3, v217
	s_and_saveexec_b64 s[4:5], vcc
	s_cbranch_execz .LBB0_1040
	s_add_i32 s3, 0, 0x23f20
	v_mov_b32_e32 v3, s3
	s_waitcnt vmcnt(0) expcnt(0) lgkmcnt(0)
	ds_read_b32 v5, v3
	s_add_i32 s3, 0, 0x23f24
	v_mov_b32_e32 v3, s3
	ds_read_b32 v3, v3
	s_waitcnt lgkmcnt(1)
	v_cmp_ne_u32_e32 vcc, 0, v5
	s_cbranch_vccnz .LBB0_1004
	s_add_u32 s6, s82, 0x40200
	s_addc_u32 s7, s83, 0
	s_add_u32 s8, s82, 0x40400
	s_addc_u32 s9, s83, 0
	s_add_u32 s10, s82, 0x40500
	s_addc_u32 s11, s83, 0
	s_add_u32 s12, s82, 0x40600
	s_addc_u32 s13, s83, 0
	s_add_u32 s16, s82, 0x40700
	s_addc_u32 s17, s83, 0
	s_add_u32 s18, s82, 0x40800
	s_addc_u32 s19, s83, 0
	s_add_u32 s20, s82, 0x40900
	s_addc_u32 s21, s83, 0
	s_add_u32 s22, s82, 0x40a00
	s_addc_u32 s23, s83, 0
	s_add_u32 s24, s82, 0x40b00
	s_addc_u32 s25, s83, 0
	s_add_u32 s26, s82, 0x40c00
	s_addc_u32 s27, s83, 0
	s_add_u32 s28, s82, 0x40d00
	s_addc_u32 s29, s83, 0
	s_add_u32 s30, s82, 0x40e00
	s_addc_u32 s31, s83, 0
	s_add_u32 s34, s82, 0x40f00
	s_addc_u32 s35, s83, 0
	s_add_u32 s36, s82, 0x41000
	s_addc_u32 s37, s83, 0
	s_add_u32 s38, s82, 0x41100
	s_addc_u32 s39, s83, 0
	s_add_u32 s40, s82, 0x41200
	v_readlane_b32 s3, v244, 2
	s_addc_u32 s41, s83, 0
	s_mul_i32 s3, s89, s3
	s_add_u32 s42, s82, 0x41300
	s_mul_i32 s3, s3, s88
	s_addc_u32 s43, s83, 0
	s_mov_b32 s33, 1
	v_mov_b32_e32 v19, 0
	s_branch .LBB0_992

.LBB0_1170:
	v_readlane_b32 s0, v244, 3
	v_readlane_b32 s1, v244, 4
	s_cmp_gt_i32 s1, 7
	s_cselect_b64 s[0:1], -1, 0
	s_and_b64 s[4:5], s[8:9], s[0:1]
	s_andn2_b64 vcc, exec, s[4:5]
	s_cbranch_vccnz .LBB0_1224
	s_waitcnt vmcnt(0)
	s_waitcnt vmcnt(0)
	s_barrier
	s_getreg_b32 s3, hwreg(HW_REG_HW_ID, 0, 6)
	s_and_b32 s3, s3, 63
	s_lshl_b32 s3, s3, 2
	s_add_i32 s3, s3, 0
	s_mov_b64 s[4:5], src_shared_base
	s_add_i32 s3, s3, 0x23e00
	v_mov_b32_e32 v4, s3
	v_mov_b32_e32 v5, s5
	flat_load_dword v3, v[4:5] sc0 sc1
	s_waitcnt vmcnt(0) lgkmcnt(0)
	v_readfirstlane_b32 s3, v3
	s_cmp_lg_u32 s3, 1
	s_cbranch_scc1 .Learlyinv_skip6
	buffer_inv sc1
	s_waitcnt vmcnt(0)
.Learlyinv_skip6:
	s_lshl_b32 s3, s3, 6
	s_sub_i32 s3, 0, s3
	v_cmp_eq_u32_e32 vcc, s3, v217
	s_and_saveexec_b64 s[4:5], vcc
	s_cbranch_execz .LBB0_1223
	s_add_i32 s3, 0, 0x23f20
	v_mov_b32_e32 v3, s3
	s_waitcnt vmcnt(0) expcnt(0) lgkmcnt(0)
	ds_read_b32 v5, v3
	s_add_i32 s3, 0, 0x23f24
	v_mov_b32_e32 v3, s3
	ds_read_b32 v3, v3
	s_waitcnt lgkmcnt(1)
	v_cmp_ne_u32_e32 vcc, 0, v5
	s_cbranch_vccnz .LBB0_1187
	v_readlane_b32 s6, v244, 0
	v_readlane_b32 s7, v244, 1
	s_load_dword s6, s[6:7], 0x14
	s_mov_b32 s3, 1
	v_mov_b32_e32 v19, 0
	s_waitcnt lgkmcnt(0)
	s_lshr_b32 s8, s6, 16
	s_and_b32 s6, s6, 0xffff
	s_cmp_lg_u32 s6, 0
	s_cselect_b64 s[6:7], -1, 0
	s_cmp_lg_u64 s[6:7], 0
	s_addc_u32 s6, s89, 0
	s_cmp_lg_u32 s8, 0
	s_mul_i32 s33, s6, s88
	s_cselect_b64 s[6:7], -1, 0
	s_cmp_lg_u64 s[6:7], 0
	v_readlane_b32 s6, v244, 2
	s_addc_u32 s6, s6, 0
	s_mul_i32 s33, s33, s6
	s_add_u32 s6, s82, 0x40200
	s_addc_u32 s7, s83, 0
	s_add_u32 s8, s82, 0x40400
	s_addc_u32 s9, s83, 0
	s_add_u32 s10, s82, 0x40500
	s_addc_u32 s11, s83, 0
	s_add_u32 s12, s82, 0x40600
	s_addc_u32 s13, s83, 0
	s_add_u32 s14, s82, 0x40700
	s_addc_u32 s15, s83, 0
	s_add_u32 s16, s82, 0x40800
	s_addc_u32 s17, s83, 0
	s_add_u32 s18, s82, 0x40900
	s_addc_u32 s19, s83, 0
	s_add_u32 s20, s82, 0x40a00
	s_addc_u32 s21, s83, 0
	s_add_u32 s22, s82, 0x40b00
	s_addc_u32 s23, s83, 0
	s_add_u32 s24, s82, 0x40c00
	s_addc_u32 s25, s83, 0
	s_add_u32 s26, s82, 0x40d00
	s_addc_u32 s27, s83, 0
	s_add_u32 s28, s82, 0x40e00
	s_addc_u32 s29, s83, 0
	s_add_u32 s30, s82, 0x40f00
	s_addc_u32 s31, s83, 0
	s_add_u32 s34, s82, 0x41000
	s_addc_u32 s35, s83, 0
	s_add_u32 s36, s82, 0x41100
	s_addc_u32 s37, s83, 0
	s_add_u32 s38, s82, 0x41200
	s_addc_u32 s39, s83, 0
	s_add_u32 s40, s82, 0x41300
	s_addc_u32 s41, s83, 0
	s_branch .LBB0_1175

.LBB0_1507:
	v_readlane_b32 s0, v244, 3
	v_readlane_b32 s1, v244, 4
	s_cmp_gt_i32 s1, 8
	s_cselect_b64 s[0:1], -1, 0
	s_and_b64 s[4:5], s[4:5], s[0:1]
	s_andn2_b64 vcc, exec, s[4:5]
	s_cbranch_vccnz .LBB0_1561
	s_waitcnt vmcnt(0)
	s_waitcnt vmcnt(0)
	s_barrier
	s_getreg_b32 s3, hwreg(HW_REG_HW_ID, 0, 6)
	s_and_b32 s3, s3, 63
	s_lshl_b32 s3, s3, 2
	s_add_i32 s3, s3, 0
	s_mov_b64 s[4:5], src_shared_base
	s_add_i32 s3, s3, 0x23e00
	v_mov_b32_e32 v2, s3
	v_mov_b32_e32 v3, s5
	flat_load_dword v2, v[2:3] sc0 sc1
	s_waitcnt vmcnt(0) lgkmcnt(0)
	v_readfirstlane_b32 s3, v2
	s_cmp_lg_u32 s3, 1
	s_cbranch_scc1 .Learlyinv_skip7
	buffer_inv sc1
	s_waitcnt vmcnt(0)
.Learlyinv_skip7:
	s_lshl_b32 s3, s3, 6
	s_sub_i32 s3, 0, s3
	v_cmp_eq_u32_e32 vcc, s3, v217
	s_and_saveexec_b64 s[4:5], vcc
	s_cbranch_execz .LBB0_1560
	s_add_i32 s3, 0, 0x23f20
	v_mov_b32_e32 v2, s3
	s_waitcnt vmcnt(0) expcnt(0) lgkmcnt(0)
	ds_read_b32 v4, v2
	s_add_i32 s3, 0, 0x23f24
	v_mov_b32_e32 v2, s3
	ds_read_b32 v2, v2
	s_waitcnt lgkmcnt(1)
	v_cmp_ne_u32_e32 vcc, 0, v4
	s_cbranch_vccnz .LBB0_1524
	v_readlane_b32 s6, v244, 0
	v_readlane_b32 s7, v244, 1
	s_load_dword s6, s[6:7], 0x14
	s_mov_b32 s3, 1
	v_mov_b32_e32 v18, 0
	s_waitcnt lgkmcnt(0)
	s_lshr_b32 s8, s6, 16
	s_and_b32 s6, s6, 0xffff
	s_cmp_lg_u32 s6, 0
	s_cselect_b64 s[6:7], -1, 0
	s_cmp_lg_u64 s[6:7], 0
	s_addc_u32 s6, s89, 0
	s_cmp_lg_u32 s8, 0
	s_mul_i32 s33, s6, s88
	s_cselect_b64 s[6:7], -1, 0
	s_cmp_lg_u64 s[6:7], 0
	v_readlane_b32 s6, v244, 2
	s_addc_u32 s6, s6, 0
	s_mul_i32 s33, s33, s6
	s_add_u32 s6, s82, 0x40200
	s_addc_u32 s7, s83, 0
	s_add_u32 s8, s82, 0x40400
	s_addc_u32 s9, s83, 0
	s_add_u32 s10, s82, 0x40500
	s_addc_u32 s11, s83, 0
	s_add_u32 s12, s82, 0x40600
	s_addc_u32 s13, s83, 0
	s_add_u32 s14, s82, 0x40700
	s_addc_u32 s15, s83, 0
	s_add_u32 s16, s82, 0x40800
	s_addc_u32 s17, s83, 0
	s_add_u32 s18, s82, 0x40900
	s_addc_u32 s19, s83, 0
	s_add_u32 s20, s82, 0x40a00
	s_addc_u32 s21, s83, 0
	s_add_u32 s22, s82, 0x40b00
	s_addc_u32 s23, s83, 0
	s_add_u32 s24, s82, 0x40c00
	s_addc_u32 s25, s83, 0
	s_add_u32 s26, s82, 0x40d00
	s_addc_u32 s27, s83, 0
	s_add_u32 s28, s82, 0x40e00
	s_addc_u32 s29, s83, 0
	s_add_u32 s30, s82, 0x40f00
	s_addc_u32 s31, s83, 0
	s_add_u32 s34, s82, 0x41000
	s_addc_u32 s35, s83, 0
	s_add_u32 s36, s82, 0x41100
	s_addc_u32 s37, s83, 0
	s_add_u32 s38, s82, 0x41200
	s_addc_u32 s39, s83, 0
	s_add_u32 s40, s82, 0x41300
	s_addc_u32 s41, s83, 0
	s_branch .LBB0_1512

.LBB0_1557:
	s_or_b64 exec, exec, s[8:9]
	s_mov_b64 s[8:9], exec
	v_mbcnt_lo_u32_b32 v2, s8, 0
	v_mbcnt_hi_u32_b32 v2, s9, v2
	v_cmp_eq_u32_e32 vcc, 0, v2
	s_waitcnt vmcnt(0)
	s_and_saveexec_b64 s[10:11], vcc
	s_cbranch_execz .LBB0_1559
	s_bcnt1_i32_b64 s3, s[8:9]
	v_mov_b32_e32 v2, 0x2000
	v_mov_b32_e32 v3, s3
	global_atomic_add v2, v3, s[6:7] offset:1024

.LBB0_1663:
	v_readlane_b32 s0, v244, 3
	v_readlane_b32 s1, v244, 4
	s_cmp_gt_i32 s1, 9
	s_cselect_b64 s[0:1], -1, 0
	s_and_b64 s[4:5], s[8:9], s[0:1]
	s_andn2_b64 vcc, exec, s[4:5]
	s_cbranch_vccnz .LBB0_1717
	s_waitcnt vmcnt(0)
	s_waitcnt vmcnt(0) lgkmcnt(0)
	s_barrier
	s_getreg_b32 s3, hwreg(HW_REG_HW_ID, 0, 6)
	s_and_b32 s3, s3, 63
	s_lshl_b32 s3, s3, 2
	s_add_i32 s3, s3, 0
	s_mov_b64 s[4:5], src_shared_base
	s_add_i32 s3, s3, 0x23e00
	v_mov_b32_e32 v2, s3
	v_mov_b32_e32 v3, s5
	flat_load_dword v2, v[2:3] sc0 sc1
	s_waitcnt vmcnt(0) lgkmcnt(0)
	v_readfirstlane_b32 s3, v2
	s_cmp_lg_u32 s3, 1
	s_cbranch_scc1 .Learlyinv_skip8
	buffer_inv sc1
	s_waitcnt vmcnt(0)

.LBB0_1760:
	v_readlane_b32 s0, v244, 3
	v_readlane_b32 s1, v244, 4
	s_cmp_gt_i32 s1, 10
	s_cselect_b64 s[0:1], -1, 0
	s_and_b64 s[4:5], s[4:5], s[0:1]
	s_andn2_b64 vcc, exec, s[4:5]
	s_cbranch_vccnz .LBB0_1814
	s_waitcnt vmcnt(0)
	s_waitcnt vmcnt(0) lgkmcnt(0)
	s_barrier
	s_getreg_b32 s3, hwreg(HW_REG_HW_ID, 0, 6)
	s_and_b32 s3, s3, 63
	s_lshl_b32 s3, s3, 2
	s_add_i32 s3, s3, 0
	s_mov_b64 s[4:5], src_shared_base
	s_add_i32 s3, s3, 0x23e00
	v_mov_b32_e32 v2, s3
	v_mov_b32_e32 v3, s5
	flat_load_dword v2, v[2:3] sc0 sc1
	s_waitcnt vmcnt(0) lgkmcnt(0)
	v_readfirstlane_b32 s3, v2
	s_cmp_lg_u32 s3, 1
	s_cbranch_scc1 .Learlyinv_skip9
	buffer_inv sc1
	s_waitcnt vmcnt(0)
.Learlyinv_skip9:
	s_lshl_b32 s3, s3, 6
	s_sub_i32 s3, 0, s3
	v_cmp_eq_u32_e32 vcc, s3, v217
	s_and_saveexec_b64 s[4:5], vcc
	s_cbranch_execz .LBB0_1813
	s_add_i32 s3, 0, 0x23f20
	v_mov_b32_e32 v2, s3
	s_waitcnt vmcnt(0) expcnt(0) lgkmcnt(0)
	ds_read_b32 v4, v2
	s_add_i32 s3, 0, 0x23f24
	v_mov_b32_e32 v2, s3
	ds_read_b32 v2, v2
	s_waitcnt lgkmcnt(1)
	v_cmp_ne_u32_e32 vcc, 0, v4
	s_cbranch_vccnz .LBB0_1777
	s_add_u32 s6, s82, 0x40200
	s_addc_u32 s7, s83, 0
	s_add_u32 s8, s82, 0x40400
	s_addc_u32 s9, s83, 0
	s_add_u32 s10, s82, 0x40500
	s_addc_u32 s11, s83, 0
	s_add_u32 s12, s82, 0x40600
	s_addc_u32 s13, s83, 0
	s_add_u32 s14, s82, 0x40700
	s_addc_u32 s15, s83, 0
	s_add_u32 s16, s82, 0x40800
	s_addc_u32 s17, s83, 0
	s_add_u32 s18, s82, 0x40900
	s_addc_u32 s19, s83, 0
	s_add_u32 s20, s82, 0x40a00
	s_addc_u32 s21, s83, 0
	s_add_u32 s22, s82, 0x40b00
	s_addc_u32 s23, s83, 0
	s_add_u32 s24, s82, 0x40c00
	s_addc_u32 s25, s83, 0
	s_add_u32 s26, s82, 0x40d00
	s_addc_u32 s27, s83, 0
	s_add_u32 s28, s82, 0x40e00
	s_addc_u32 s29, s83, 0
	s_add_u32 s30, s82, 0x40f00
	s_addc_u32 s31, s83, 0
	s_add_u32 s34, s82, 0x41000
	s_addc_u32 s35, s83, 0
	s_add_u32 s36, s82, 0x41100
	s_addc_u32 s37, s83, 0
	s_add_u32 s38, s82, 0x41200
	v_readlane_b32 s3, v244, 2
	s_addc_u32 s39, s83, 0
	s_mul_i32 s3, s89, s3
	s_add_u32 s40, s82, 0x41300
	s_mul_i32 s3, s3, s88
	s_addc_u32 s41, s83, 0
	s_mov_b32 s33, 1
	v_mov_b32_e32 v18, 0
	s_branch .LBB0_1765
